# grid barrier: arriving non-leader workgroups also issue an L2 write-back so the XCD leader's final write-back finds the L2 mostly clean
# baseline (speedup 1.0000x reference)
.LBB0_115:
	s_or_b64 exec, exec, s[12:13]
	v_cvt_f32_u32_e32 v4, v2
	s_waitcnt vmcnt(0)
	v_readfirstlane_b32 s6, v3
	v_sub_u32_e32 v3, 0, v2
	v_rcp_iflag_f32_e32 v4, v4
	v_add_u32_e32 v5, s6, v1
	v_mul_f32_e32 v4, 0x4f7ffffe, v4
	v_cvt_u32_f32_e32 v4, v4
	v_mul_lo_u32 v1, v3, v4
	v_mul_hi_u32 v1, v4, v1
	v_add_u32_e32 v1, v4, v1
	v_mul_hi_u32 v1, v5, v1
	v_mul_lo_u32 v3, v1, v2
	v_sub_u32_e32 v3, v5, v3
	v_add_u32_e32 v4, 1, v1
	v_sub_u32_e32 v6, v3, v2
	v_cmp_ge_u32_e32 vcc, v3, v2
	s_nop 1
	v_cndmask_b32_e32 v1, v1, v4, vcc
	v_cndmask_b32_e32 v3, v3, v6, vcc
	v_add_u32_e32 v4, 1, v1
	v_cmp_ge_u32_e32 vcc, v3, v2
	v_add_u32_e32 v3, 1, v5
	s_nop 0
	v_cndmask_b32_e32 v1, v1, v4, vcc
	v_mul_lo_u32 v4, v2, v1
	v_add_u32_e32 v2, v4, v2
	v_cmp_ne_u32_e32 vcc, v3, v2
	s_and_saveexec_b64 s[6:7], vcc
	s_xor_b64 s[12:13], exec, s[6:7]
	s_cbranch_execz .LBB0_129
	v_readlane_b32 s100, v252, 9
	s_nop 3
	v_mov_b32_e32 v18, s100
	ds_read_b32 v18, v18
	v_add_u32_e32 v19, 1, v1
	s_waitcnt lgkmcnt(0)
	v_mul_lo_u32 v18, v18, v19
	v_readlane_b32 s6, v253, 20
	v_readlane_b32 s7, v253, 21
	s_waitcnt lgkmcnt(0)
	s_nop 3
	buffer_wbl2 sc1
	buffer_inv sc1
	global_load_dword v0, v64, s[6:7] sc1
	s_waitcnt vmcnt(0)
	v_cmp_lt_u32_e32 vcc, v0, v18
	s_and_saveexec_b64 s[16:17], vcc
	s_cbranch_execz .LBB0_128
	s_mov_b32 s6, 1
	s_mov_b64 s[20:21], 0
	s_branch .LBB0_119

.LBB0_1155:
	s_or_b64 exec, exec, s[12:13]
	v_cvt_f32_u32_e32 v4, v2
	s_waitcnt vmcnt(0)
	v_readfirstlane_b32 s6, v3
	v_sub_u32_e32 v3, 0, v2
	v_rcp_iflag_f32_e32 v4, v4
	v_add_u32_e32 v5, s6, v1
	v_mul_f32_e32 v4, 0x4f7ffffe, v4
	v_cvt_u32_f32_e32 v4, v4
	v_mul_lo_u32 v1, v3, v4
	v_mul_hi_u32 v1, v4, v1
	v_add_u32_e32 v1, v4, v1
	v_mul_hi_u32 v1, v5, v1
	v_mul_lo_u32 v3, v1, v2
	v_sub_u32_e32 v3, v5, v3
	v_add_u32_e32 v4, 1, v1
	v_cmp_ge_u32_e32 vcc, v3, v2
	s_nop 1
	v_cndmask_b32_e32 v1, v1, v4, vcc
	v_sub_u32_e32 v4, v3, v2
	v_cndmask_b32_e32 v3, v3, v4, vcc
	v_add_u32_e32 v4, 1, v1
	v_cmp_ge_u32_e32 vcc, v3, v2
	v_add_u32_e32 v3, 1, v5
	s_nop 0
	v_cndmask_b32_e32 v1, v1, v4, vcc
	v_mul_lo_u32 v4, v2, v1
	v_add_u32_e32 v2, v4, v2
	v_cmp_ne_u32_e32 vcc, v3, v2
	s_and_saveexec_b64 s[6:7], vcc
	s_xor_b64 s[12:13], exec, s[6:7]
	s_cbranch_execz .LBB0_1169
	v_readlane_b32 s100, v252, 9
	s_nop 3
	v_mov_b32_e32 v18, s100
	ds_read_b32 v18, v18
	v_add_u32_e32 v19, 1, v1
	s_waitcnt lgkmcnt(0)
	v_mul_lo_u32 v18, v18, v19
	v_readlane_b32 s6, v253, 20
	v_readlane_b32 s7, v253, 21
	s_waitcnt lgkmcnt(0)
	s_nop 3
	buffer_wbl2 sc1
	buffer_inv sc1
	global_load_dword v0, v64, s[6:7] sc1
	s_waitcnt vmcnt(0)
	v_cmp_lt_u32_e32 vcc, v0, v18
	s_and_saveexec_b64 s[16:17], vcc
	s_cbranch_execz .LBB0_1168
	s_mov_b32 s6, 1
	s_mov_b64 s[20:21], 0
	s_branch .LBB0_1159

.LBB0_1797:
	s_or_b64 exec, exec, s[12:13]
	v_cvt_f32_u32_e32 v4, v2
	s_waitcnt vmcnt(0)
	v_readfirstlane_b32 s2, v3
	v_sub_u32_e32 v3, 0, v2
	v_rcp_iflag_f32_e32 v4, v4
	v_add_u32_e32 v5, s2, v1
	v_mul_f32_e32 v4, 0x4f7ffffe, v4
	v_cvt_u32_f32_e32 v4, v4
	v_mul_lo_u32 v1, v3, v4
	v_mul_hi_u32 v1, v4, v1
	v_add_u32_e32 v1, v4, v1
	v_mul_hi_u32 v1, v5, v1
	v_mul_lo_u32 v3, v1, v2
	v_sub_u32_e32 v3, v5, v3
	v_add_u32_e32 v4, 1, v1
	v_cmp_ge_u32_e32 vcc, v3, v2
	s_nop 1
	v_cndmask_b32_e32 v1, v1, v4, vcc
	v_sub_u32_e32 v4, v3, v2
	v_cndmask_b32_e32 v3, v3, v4, vcc
	v_add_u32_e32 v4, 1, v1
	v_cmp_ge_u32_e32 vcc, v3, v2
	v_add_u32_e32 v3, 1, v5
	s_nop 0
	v_cndmask_b32_e32 v1, v1, v4, vcc
	v_mul_lo_u32 v4, v2, v1
	v_add_u32_e32 v2, v4, v2
	v_cmp_ne_u32_e32 vcc, v3, v2
	s_and_saveexec_b64 s[2:3], vcc
	s_xor_b64 s[12:13], exec, s[2:3]
	s_cbranch_execz .LBB0_1811
	v_readlane_b32 s100, v252, 9
	s_nop 3
	v_mov_b32_e32 v18, s100
	ds_read_b32 v18, v18
	v_add_u32_e32 v19, 1, v1
	s_waitcnt lgkmcnt(0)
	v_mul_lo_u32 v18, v18, v19
	v_readlane_b32 s2, v253, 20
	v_readlane_b32 s3, v253, 21
	s_waitcnt lgkmcnt(0)
	s_nop 3
	buffer_wbl2 sc1
	buffer_inv sc1
	global_load_dword v0, v64, s[2:3] sc1
	s_waitcnt vmcnt(0)
	v_cmp_lt_u32_e32 vcc, v0, v18
	s_and_saveexec_b64 s[20:21], vcc
	s_cbranch_execz .LBB0_1810
	s_mov_b32 s2, 1
	s_mov_b64 s[28:29], 0
	s_branch .LBB0_1801

.LBB0_1924:
	s_or_b64 exec, exec, s[12:13]
	v_cvt_f32_u32_e32 v4, v2
	s_waitcnt vmcnt(0)
	v_readfirstlane_b32 s2, v3
	v_sub_u32_e32 v3, 0, v2
	v_rcp_iflag_f32_e32 v4, v4
	v_add_u32_e32 v5, s2, v1
	v_mul_f32_e32 v4, 0x4f7ffffe, v4
	v_cvt_u32_f32_e32 v4, v4
	v_mul_lo_u32 v1, v3, v4
	v_mul_hi_u32 v1, v4, v1
	v_add_u32_e32 v1, v4, v1
	v_mul_hi_u32 v1, v5, v1
	v_mul_lo_u32 v3, v1, v2
	v_sub_u32_e32 v3, v5, v3
	v_add_u32_e32 v4, 1, v1
	v_cmp_ge_u32_e32 vcc, v3, v2
	s_nop 1
	v_cndmask_b32_e32 v1, v1, v4, vcc
	v_sub_u32_e32 v4, v3, v2
	v_cndmask_b32_e32 v3, v3, v4, vcc
	v_add_u32_e32 v4, 1, v1
	v_cmp_ge_u32_e32 vcc, v3, v2
	v_add_u32_e32 v3, 1, v5
	s_nop 0
	v_cndmask_b32_e32 v1, v1, v4, vcc
	v_mul_lo_u32 v4, v2, v1
	v_add_u32_e32 v2, v4, v2
	v_cmp_ne_u32_e32 vcc, v3, v2
	s_and_saveexec_b64 s[2:3], vcc
	s_xor_b64 s[12:13], exec, s[2:3]
	s_cbranch_execz .LBB0_1938
	v_readlane_b32 s100, v252, 9
	s_nop 3
	v_mov_b32_e32 v18, s100
	ds_read_b32 v18, v18
	v_add_u32_e32 v19, 1, v1
	s_waitcnt lgkmcnt(0)
	v_mul_lo_u32 v18, v18, v19
	v_readlane_b32 s2, v253, 20
	v_readlane_b32 s3, v253, 21
	s_waitcnt lgkmcnt(0)
	s_nop 3
	buffer_wbl2 sc1
	buffer_inv sc1
	global_load_dword v0, v64, s[2:3] sc1
	s_waitcnt vmcnt(0)
	v_cmp_lt_u32_e32 vcc, v0, v18
	s_and_saveexec_b64 s[20:21], vcc
	s_cbranch_execz .LBB0_1937
	s_mov_b32 s2, 1
	s_mov_b64 s[42:43], 0
	s_branch .LBB0_1928

.LBB0_2187:
	s_or_b64 exec, exec, s[12:13]
	v_cvt_f32_u32_e32 v4, v2
	s_waitcnt vmcnt(0)
	v_readfirstlane_b32 s2, v3
	v_sub_u32_e32 v3, 0, v2
	v_rcp_iflag_f32_e32 v4, v4
	v_add_u32_e32 v5, s2, v1
	v_mul_f32_e32 v4, 0x4f7ffffe, v4
	v_cvt_u32_f32_e32 v4, v4
	v_mul_lo_u32 v1, v3, v4
	v_mul_hi_u32 v1, v4, v1
	v_add_u32_e32 v1, v4, v1
	v_mul_hi_u32 v1, v5, v1
	v_mul_lo_u32 v3, v1, v2
	v_sub_u32_e32 v3, v5, v3
	v_add_u32_e32 v4, 1, v1
	v_cmp_ge_u32_e32 vcc, v3, v2
	s_nop 1
	v_cndmask_b32_e32 v1, v1, v4, vcc
	v_sub_u32_e32 v4, v3, v2
	v_cndmask_b32_e32 v3, v3, v4, vcc
	v_add_u32_e32 v4, 1, v1
	v_cmp_ge_u32_e32 vcc, v3, v2
	v_add_u32_e32 v3, 1, v5
	s_nop 0
	v_cndmask_b32_e32 v1, v1, v4, vcc
	v_mul_lo_u32 v4, v2, v1
	v_add_u32_e32 v2, v4, v2
	v_cmp_ne_u32_e32 vcc, v3, v2
	s_and_saveexec_b64 s[2:3], vcc
	s_xor_b64 s[12:13], exec, s[2:3]
	s_cbranch_execz .LBB0_2201
	v_readlane_b32 s100, v252, 9
	s_nop 3
	v_mov_b32_e32 v18, s100
	ds_read_b32 v18, v18
	v_add_u32_e32 v19, 1, v1
	s_waitcnt lgkmcnt(0)
	v_mul_lo_u32 v18, v18, v19
	v_readlane_b32 s2, v253, 20
	v_readlane_b32 s3, v253, 21
	s_waitcnt lgkmcnt(0)
	s_nop 3
	buffer_wbl2 sc1
	buffer_inv sc1
	global_load_dword v0, v64, s[2:3] sc1
	s_waitcnt vmcnt(0)
	v_cmp_lt_u32_e32 vcc, v0, v18
	s_and_saveexec_b64 s[16:17], vcc
	s_cbranch_execz .LBB0_2200
	s_mov_b32 s2, 1
	s_mov_b64 s[20:21], 0
	s_branch .LBB0_2191

.LBB0_2261:
	s_or_b64 exec, exec, s[6:7]
	v_cvt_f32_u32_e32 v4, v2
	s_waitcnt vmcnt(0)
	v_readfirstlane_b32 s6, v3
	v_sub_u32_e32 v3, 0, v2
	v_rcp_iflag_f32_e32 v4, v4
	v_add_u32_e32 v5, s6, v1
	v_mul_f32_e32 v4, 0x4f7ffffe, v4
	v_cvt_u32_f32_e32 v4, v4
	v_mul_lo_u32 v1, v3, v4
	v_mul_hi_u32 v1, v4, v1
	v_add_u32_e32 v1, v4, v1
	v_mul_hi_u32 v1, v5, v1
	v_mul_lo_u32 v3, v1, v2
	v_sub_u32_e32 v3, v5, v3
	v_add_u32_e32 v4, 1, v1
	v_cmp_ge_u32_e32 vcc, v3, v2
	s_nop 1
	v_cndmask_b32_e32 v1, v1, v4, vcc
	v_sub_u32_e32 v4, v3, v2
	v_cndmask_b32_e32 v3, v3, v4, vcc
	v_add_u32_e32 v4, 1, v1
	v_cmp_ge_u32_e32 vcc, v3, v2
	v_add_u32_e32 v3, 1, v5
	s_nop 0
	v_cndmask_b32_e32 v1, v1, v4, vcc
	v_mul_lo_u32 v4, v2, v1
	v_add_u32_e32 v2, v4, v2
	v_cmp_ne_u32_e32 vcc, v3, v2
	s_and_saveexec_b64 s[6:7], vcc
	s_xor_b64 s[6:7], exec, s[6:7]
	s_cbranch_execz .LBB0_2275
	v_readlane_b32 s100, v252, 9
	s_nop 3
	v_mov_b32_e32 v18, s100
	ds_read_b32 v18, v18
	v_add_u32_e32 v19, 1, v1
	s_waitcnt lgkmcnt(0)
	v_mul_lo_u32 v18, v18, v19
	v_readlane_b32 s12, v253, 20
	v_readlane_b32 s13, v253, 21
	s_waitcnt lgkmcnt(0)
	s_nop 3
	buffer_wbl2 sc1
	buffer_inv sc1
	global_load_dword v0, v64, s[12:13] sc1
	s_waitcnt vmcnt(0)
	v_cmp_lt_u32_e32 vcc, v0, v18
	s_and_saveexec_b64 s[12:13], vcc
	s_cbranch_execz .LBB0_2274
	s_mov_b32 s18, 1
	s_mov_b64 s[16:17], 0
	s_branch .LBB0_2265
